# ag_rows strips spread over all blocks (one strip per wave after pass A) instead of the 16 conv blocks; conv tile split moved to 3872
# speedup vs baseline: 1.0339x; 1.0131x over previous
.LBB0_366:
	s_add_i32 s95, s50, 0xffffff10
	s_cmp_ge_i32 s33, s50
	s_cselect_b64 s[0:1], -1, 0
	s_mov_b64 s[2:3], 0
	s_or_b64 s[0:1], s[2:3], s[0:1]
	s_and_b64 vcc, exec, s[0:1]
	s_cbranch_vccnz .LBB0_469
	s_lshl_b32 s0, s33, 3
	v_lshrrev_b32_e32 v12, 6, v188
	s_nop 0
	v_add_u32_e32 v128, s0, v12
	s_movk_i32 s0, 0x410
	v_cmp_gt_i32_e32 vcc, s0, v128
	s_mov_b64 s[0:1], exec
	v_writelane_b32 v254, s0, 31
	s_nop 1
	v_writelane_b32 v254, s1, 32
	s_and_b64 s[0:1], s[0:1], vcc
	s_mov_b64 exec, s[0:1]
	s_cbranch_execz .LBB0_468
	v_mov_b32_e32 v3, 0
	v_lshlrev_b32_e32 v2, 3, v1
	v_lshlrev_b32_e32 v14, 1, v1
	v_lshl_add_u64 v[4:5], s[76:77], 0, v[2:3]
	v_or_b32_e32 v10, 0xa00, v14
	v_add_co_u32_e32 v6, vcc, 0x5000, v4
	v_lshlrev_b32_e32 v8, 2, v10
	s_nop 0
	v_addc_co_u32_e32 v7, vcc, 0, v5, vcc
	global_load_dwordx2 v[4:5], v8, s[76:77]
	s_nop 0
	global_load_dwordx2 v[6:7], v[6:7], off offset:512
	v_lshl_add_u64 v[8:9], s[88:89], 0, v[2:3]
	v_lshlrev_b32_e32 v2, 1, v10
	s_add_u32 s62, s88, 0xce40000
	v_lshrrev_b32_e32 v13, 4, v1
	v_lshl_add_u64 v[10:11], s[88:89], 0, v[2:3]
	v_lshlrev_b32_e32 v2, 4, v12
	s_addc_u32 s63, s89, 0
	v_lshlrev_b32_e32 v16, 2, v1
	v_lshlrev_b32_e64 v129, v13, 1
	v_lshl_add_u32 v2, s33, 7, v2
	s_lshl_b32 s49, s50, 7
	s_lshl_b32 s48, s50, 3
	v_cmp_eq_u32_e64 s[2:3], 3, v13
	v_cmp_gt_u32_e64 s[4:5], 16, v1
	v_cmp_eq_u32_e64 s[6:7], 1, v13
	v_cmp_eq_u32_e64 s[8:9], 2, v13
	v_add_u32_e32 v130, -8, v2
	s_nop 0
	v_sub_u32_e32 v131, 0, v129
	s_mov_b64 s[80:81], 0
	v_mov_b32_e32 v132, 0xffffc000
	v_mov_b32_e32 v133, 0x100
	v_mov_b32_e32 v134, 0x4000
	s_movk_i32 s92, 0x1800
	s_mov_b32 s93, 0xffff0000
	s_movk_i32 s0, 0x7fff
	s_movk_i32 s1, 0x300
	v_lshlrev_b32_e32 v2, 1, v14
	v_lshlrev_b32_e32 v12, 1, v16
	v_mov_b32_e32 v135, 1
	s_branch .LBB0_370

.LBB0_469:
	s_add_i32 s0, s33, 0xffffff10
	s_cmpk_gt_u32 s0, 0xc3f
	s_cbranch_scc1 .LBB0_492
	v_lshlrev_b32_e32 v2, 2, v1
	v_lshrrev_b32_e32 v3, 3, v188
	v_add_u32_e32 v39, 0, v2
	v_readlane_b32 s8, v254, 0
	v_and_b32_e32 v26, 0x78, v3
	v_or_b32_e32 v33, 7, v3
	v_lshl_add_u32 v3, v1, 8, v39
	v_readlane_b32 s9, v254, 1
	v_readlane_b32 s10, v254, 2
	v_readlane_b32 s11, v254, 3
	v_readlane_b32 s12, v254, 4
	v_readlane_b32 s13, v254, 5
	v_lshl_add_u32 v34, v26, 2, v3
	v_lshl_add_u32 v35, v33, 2, v3
	v_mov_b32_e32 v3, 0
	v_readlane_b32 s14, v254, 6
	v_readlane_b32 s15, v254, 7
	s_mov_b64 s[6:7], s[10:11]
	s_mov_b64 s[8:9], s[12:13]
	v_lshl_add_u64 v[4:5], s[8:9], 0, v[2:3]
	v_lshl_add_u64 v[6:7], s[72:73], 0, v[2:3]
	v_lshl_add_u64 v[8:9], s[70:71], 0, v[2:3]
	v_lshl_add_u64 v[10:11], s[68:69], 0, v[2:3]
	v_lshl_add_u64 v[12:13], s[6:7], 0, v[2:3]
	v_lshl_add_u64 v[14:15], s[74:75], 0, v[2:3]
	v_lshlrev_b32_e32 v2, 1, v1
	v_lshl_add_u64 v[16:17], s[86:87], 0, v[2:3]
	s_mov_b64 s[2:3], 0x1880000
	v_lshl_add_u64 v[18:19], v[16:17], 0, s[2:3]
	s_mov_b64 s[2:3], 0x1300000
	s_add_i32 s4, s33, 0x1f0
	v_mul_u32_u24_e32 v38, 0x104, v26
	s_mov_b64 s[10:11], s[14:15]
	v_lshl_add_u64 v[20:21], v[16:17], 0, s[2:3]
	s_mov_b64 s[2:3], 0x800000
	v_mul_u32_u24_e32 v40, 0x104, v33
	v_lshl_add_u64 v[22:23], v[16:17], 0, s[2:3]
	s_mov_b64 s[2:3], 0x600000
	s_lshl_b32 s6, s50, 6
	s_mul_i32 s8, s50, 0x2e000
	v_lshrrev_b32_e32 v2, 6, v188
	s_lshl_b32 s0, s4, 2
	s_lshl_b32 s10, s50, 2
	v_add_u32_e32 v38, v39, v38
	s_mov_b32 s1, 0
	v_or_b32_e32 v27, 1, v26
	v_or_b32_e32 v28, 2, v26
	v_or_b32_e32 v29, 3, v26
	v_or_b32_e32 v30, 4, v26
	v_or_b32_e32 v31, 5, v26
	v_or_b32_e32 v32, 6, v26
	v_lshl_add_u64 v[24:25], v[16:17], 0, s[2:3]
	s_lshl_b32 s5, s4, 6
	s_addk_i32 s6, 0xc400
	v_mul_u32_u24_e32 v36, 0xb80, v33
	s_mul_i32 s7, s4, 0x2e000
	s_add_i32 s8, s8, 0xfd4e0000
	v_mul_u32_u24_e32 v37, 0x5c00, v2
	s_add_i32 s9, s0, 0x3cf80
	s_addk_i32 s10, 0xfc40
	v_add_u32_e32 v39, v39, v40
	s_movk_i32 s11, 0x7fff
	s_mov_b32 s12, 0xfff00
	s_mov_b32 s13, 0x40000
	v_add_u32_e32 v40, 0x400, v38
	s_branch .LBB0_472
.LBB0_471:
	s_add_i32 s4, s4, s95
	s_add_i32 s5, s5, s6
	s_add_i32 s7, s7, s8
	s_add_i32 s9, s9, s10
	s_cmpk_lt_i32 s4, 0xf20
	s_cbranch_scc0 .LBB0_492

.LBB0_731:
	s_add_i32 s0, s33, 0xffffff10
	s_cmpk_gt_u32 s0, 0x93f
	s_cbranch_scc1 .LBB0_770
	v_lshlrev_b32_e32 v2, 2, v1
	v_lshrrev_b32_e32 v3, 3, v188
	v_add_u32_e32 v52, 0, v2
	v_and_b32_e32 v40, 0x78, v3
	v_or_b32_e32 v47, 7, v3
	v_lshl_add_u32 v3, v1, 8, v52
	v_readlane_b32 s12, v254, 0
	v_lshl_add_u32 v48, v40, 2, v3
	v_lshl_add_u32 v49, v47, 2, v3
	v_mov_b32_e32 v3, 0
	v_readlane_b32 s14, v254, 2
	v_readlane_b32 s15, v254, 3
	v_readlane_b32 s16, v254, 4
	v_readlane_b32 s17, v254, 5
	v_lshl_add_u64 v[4:5], s[84:85], 0, v[2:3]
	v_lshl_add_u64 v[8:9], s[72:73], 0, v[2:3]
	v_lshl_add_u64 v[6:7], s[16:17], 0, v[2:3]
	v_lshl_add_u64 v[10:11], s[70:71], 0, v[2:3]
	v_lshl_add_u64 v[12:13], s[68:69], 0, v[2:3]
	v_lshl_add_u64 v[14:15], s[14:15], 0, v[2:3]
	v_lshl_add_u64 v[16:17], s[74:75], 0, v[2:3]
	v_lshlrev_b32_e32 v2, 1, v1
	s_mov_b64 s[2:3], 0xb00000
	v_lshl_add_u64 v[18:19], s[86:87], 0, v[2:3]
	v_lshl_add_u64 v[20:21], v[8:9], 0, s[2:3]
	v_lshl_add_u64 v[24:25], v[10:11], 0, s[2:3]
	v_lshl_add_u64 v[28:29], v[12:13], 0, s[2:3]
	s_mov_b64 s[2:3], 0x1e80000
	v_lshl_add_u64 v[30:31], v[18:19], 0, s[2:3]
	s_mov_b64 s[2:3], 0x1880000
	s_mov_b64 s[6:7], 0x2b80000
	v_lshl_add_u64 v[32:33], v[18:19], 0, s[2:3]
	s_mov_b64 s[2:3], 0x1300000
	s_add_i32 s4, s33, 0xe30
	v_mul_u32_u24_e32 v51, 0x104, v40
	v_readlane_b32 s13, v254, 1
	v_lshl_add_u64 v[22:23], v[18:19], 0, s[6:7]
	s_mov_b64 s[6:7], 0x2080000
	v_lshl_add_u64 v[34:35], v[18:19], 0, s[2:3]
	s_mov_b64 s[2:3], 0x800000
	v_mul_u32_u24_e32 v53, 0x104, v47
	v_lshl_add_u64 v[26:27], v[18:19], 0, s[6:7]
	v_lshl_add_u64 v[36:37], v[18:19], 0, s[2:3]
	s_mov_b64 s[2:3], 0x600000
	s_lshl_b32 s7, s50, 6
	s_mul_i32 s9, s50, 0x2e000
	v_lshrrev_b32_e32 v2, 6, v188
	s_lshl_b32 s0, s4, 2
	s_lshl_b32 s13, s50, 2
	v_add_u32_e32 v51, v52, v51
	s_mov_b32 s1, 0
	v_or_b32_e32 v41, 1, v40
	v_or_b32_e32 v42, 2, v40
	v_or_b32_e32 v43, 3, v40
	v_or_b32_e32 v44, 4, v40
	v_or_b32_e32 v45, 5, v40
	v_or_b32_e32 v46, 6, v40
	s_add_i32 s5, s50, 0xffffff10
	v_lshl_add_u64 v[38:39], v[18:19], 0, s[2:3]
	s_lshl_b32 s6, s4, 6
	s_addk_i32 s7, 0xc400
	v_mul_u32_u24_e32 v1, 0xb80, v47
	s_mul_i32 s8, s4, 0x2e000
	s_add_i32 s9, s9, 0xfd4e0000
	v_mul_u32_u24_e32 v50, 0x5c00, v2
	s_add_i32 s12, s0, 0x3b480
	s_addk_i32 s13, 0xfc40
	v_add_u32_e32 v52, v52, v53
	s_movk_i32 s14, 0x7fff
	s_mov_b32 s15, 0xfff00
	s_mov_b32 s16, 0x40000
	v_add_u32_e32 v53, 0x400, v51
	v_readlane_b32 s18, v254, 6
	v_readlane_b32 s19, v254, 7
	s_branch .LBB0_734
